# MT1 MLA latent tile loop hand-rescheduled like MT3; MT0 bias LDS reads made unconditional (exec masking removed)
# speedup vs baseline: 1.0134x; 1.0134x over previous
.LBB0_783:
	ds_read_b128 v[48:51], v184 offset:0
	ds_read_b128 v[52:55], v184 offset:32
	ds_read_b128 v[56:59], v184 offset:64
	ds_read_b128 v[60:63], v184 offset:96
	ds_read_b128 v[64:67], v184 offset:128
	ds_read_b128 v[68:71], v184 offset:160
	ds_read_b128 v[72:75], v184 offset:6656
	ds_read_b128 v[76:79], v184 offset:6688
	ds_read_b128 v[80:83], v184 offset:6720
	ds_read_b128 v[84:87], v184 offset:6752
	ds_read_b128 v[88:91], v184 offset:6784
	ds_read_b128 v[92:95], v184 offset:6816
	s_add_i32 s16, s13, 2
	s_min_u32 s6, s16, 35
	s_cmp_lt_u32 s13, 30
	s_cselect_b32 s7, 0, 0xffffffe0
	s_cselect_b32 s8, s15, s12
	s_add_i32 s7, s7, s6
	s_lshl_b32 s6, s7, 6
	s_add_i32 s8, s6, s8
	v_add_u32_e32 v208, s8, v194
	v_ashrrev_i32_e32 v209, 31, v208
	s_and_saveexec_b64 s[6:7], s[0:1]
	s_xor_b64 s[6:7], exec, s[6:7]
	v_mad_i64_i32 v[206:207], s[10:11], v208, s33, v[180:181]
	v_lshl_add_u64 v[206:207], v[206:207], 0, s[28:29]
	s_andn2_saveexec_b64 s[6:7], s[6:7]
	v_lshlrev_b64 v[206:207], 9, v[208:209]
	v_lshl_add_u64 v[206:207], v[182:183], 0, v[206:207]
	s_or_b64 exec, exec, s[6:7]
	global_load_dwordx4 v[132:135], v[206:207], off
	v_or_b32_e32 v208, s8, v195
	v_ashrrev_i32_e32 v209, 31, v208
	s_and_saveexec_b64 s[6:7], s[2:3]
	s_xor_b64 s[6:7], exec, s[6:7]
	v_mad_i64_i32 v[206:207], s[10:11], v208, s33, v[190:191]
	v_lshl_add_u64 v[206:207], v[206:207], 0, s[28:29]
	s_andn2_saveexec_b64 s[6:7], s[6:7]
	v_lshlrev_b64 v[206:207], 9, v[208:209]
	v_lshl_add_u64 v[206:207], v[192:193], 0, v[206:207]
	s_or_b64 exec, exec, s[6:7]
	global_load_dwordx4 v[136:139], v[206:207], off
	v_add_u32_e32 v206, s8, v196
	v_ashrrev_i32_e32 v207, 31, v206
	v_lshlrev_b64 v[206:207], 9, v[206:207]
	v_lshl_add_u64 v[206:207], v[178:179], 0, v[206:207]
	global_load_dwordx4 v[140:143], v[206:207], off
	s_waitcnt lgkmcnt(11)
	v_mfma_f32_32x32x16_bf16 v[144:159], v[48:51], v[96:99], v[32:47]
	s_waitcnt lgkmcnt(10)
	v_mfma_f32_32x32x16_bf16 v[144:159], v[52:55], v[100:103], v[144:159]
	s_waitcnt lgkmcnt(9)
	v_mfma_f32_32x32x16_bf16 v[144:159], v[56:59], v[104:107], v[144:159]
	s_waitcnt lgkmcnt(8)
	v_mfma_f32_32x32x16_bf16 v[144:159], v[60:63], v[108:111], v[144:159]
	s_waitcnt lgkmcnt(7)
	v_mfma_f32_32x32x16_bf16 v[144:159], v[64:67], v[112:115], v[144:159]
	s_waitcnt lgkmcnt(6)
	v_mfma_f32_32x32x16_bf16 v[144:159], v[68:71], v[116:119], v[144:159]
	s_waitcnt lgkmcnt(5)
	v_mfma_f32_32x32x16_bf16 v[160:175], v[72:75], v[96:99], v[32:47]
	s_waitcnt lgkmcnt(4)
	v_mfma_f32_32x32x16_bf16 v[160:175], v[76:79], v[100:103], v[160:175]
	s_waitcnt lgkmcnt(3)
	v_mfma_f32_32x32x16_bf16 v[160:175], v[80:83], v[104:107], v[160:175]
	s_waitcnt lgkmcnt(2)
	v_mfma_f32_32x32x16_bf16 v[160:175], v[84:87], v[108:111], v[160:175]
	s_waitcnt lgkmcnt(1)
	v_mfma_f32_32x32x16_bf16 v[160:175], v[88:91], v[112:115], v[160:175]
	s_waitcnt lgkmcnt(0)
	v_mfma_f32_32x32x16_bf16 v[160:175], v[92:95], v[116:119], v[160:175]
	ds_read_b64_tr_b16 v[48:49], v201 offset:26624
	ds_read_b64_tr_b16 v[50:51], v201 offset:28160
	ds_read_b64_tr_b16 v[52:53], v201 offset:26688
	ds_read_b64_tr_b16 v[54:55], v201 offset:28224
	ds_read_b64_tr_b16 v[56:57], v201 offset:29696
	ds_read_b64_tr_b16 v[58:59], v201 offset:31232
	ds_read_b64_tr_b16 v[60:61], v201 offset:29760
	ds_read_b64_tr_b16 v[62:63], v201 offset:31296
	ds_read_b64_tr_b16 v[64:65], v201 offset:32768
	ds_read_b64_tr_b16 v[66:67], v201 offset:34304
	ds_read_b64_tr_b16 v[68:69], v201 offset:32832
	ds_read_b64_tr_b16 v[70:71], v201 offset:34368
	ds_read_b64_tr_b16 v[72:73], v201 offset:35840
	ds_read_b64_tr_b16 v[74:75], v201 offset:37376
	ds_read_b64_tr_b16 v[76:77], v201 offset:35904
	ds_read_b64_tr_b16 v[78:79], v201 offset:37440
	v_exp_f32_e32 v144, v144
	v_exp_f32_e32 v145, v145
	v_exp_f32_e32 v146, v146
	v_exp_f32_e32 v147, v147
	v_exp_f32_e32 v148, v148
	v_exp_f32_e32 v149, v149
	v_exp_f32_e32 v150, v150
	v_exp_f32_e32 v151, v151
	v_add_f32_e32 v204, v144, v146
	v_add_f32_e32 v205, v145, v147
	v_add_f32_e32 v204, v204, v148
	v_add_f32_e32 v205, v205, v149
	v_add_f32_e32 v204, v204, v150
	v_add_f32_e32 v205, v205, v151
	v_cvt_pk_bf16_f32 v144, v144, v145
	v_cvt_pk_bf16_f32 v145, v146, v147
	v_cvt_pk_bf16_f32 v146, v148, v149
	v_cvt_pk_bf16_f32 v147, v150, v151
	v_exp_f32_e32 v152, v152
	v_exp_f32_e32 v153, v153
	s_waitcnt lgkmcnt(14)
	v_mfma_f32_32x32x16_bf16 v[16:31], v[48:51], v[144:147], v[16:31]
	v_exp_f32_e32 v154, v154
	v_exp_f32_e32 v155, v155
	v_exp_f32_e32 v156, v156
	s_waitcnt lgkmcnt(12)
	v_mfma_f32_32x32x16_bf16 v[0:15], v[52:55], v[144:147], v[0:15]
	v_exp_f32_e32 v157, v157
	v_exp_f32_e32 v158, v158
	v_exp_f32_e32 v159, v159
	v_add_f32_e32 v204, v204, v152
	v_add_f32_e32 v205, v205, v153
	v_add_f32_e32 v204, v204, v154
	v_add_f32_e32 v205, v205, v155
	v_add_f32_e32 v204, v204, v156
	v_add_f32_e32 v205, v205, v157
	v_add_f32_e32 v204, v204, v158
	v_add_f32_e32 v205, v205, v159
	v_cvt_pk_bf16_f32 v152, v152, v153
	v_cvt_pk_bf16_f32 v153, v154, v155
	v_cvt_pk_bf16_f32 v154, v156, v157
	v_cvt_pk_bf16_f32 v155, v158, v159
	v_exp_f32_e32 v160, v160
	v_exp_f32_e32 v161, v161
	s_waitcnt lgkmcnt(10)
	v_mfma_f32_32x32x16_bf16 v[16:31], v[56:59], v[152:155], v[16:31]
	v_exp_f32_e32 v162, v162
	v_exp_f32_e32 v163, v163
	v_exp_f32_e32 v164, v164
	s_waitcnt lgkmcnt(8)
	v_mfma_f32_32x32x16_bf16 v[0:15], v[60:63], v[152:155], v[0:15]
	v_exp_f32_e32 v165, v165
	v_exp_f32_e32 v166, v166
	v_exp_f32_e32 v167, v167
	v_add_f32_e32 v204, v204, v160
	v_add_f32_e32 v205, v205, v161
	v_add_f32_e32 v204, v204, v162
	v_add_f32_e32 v205, v205, v163
	v_add_f32_e32 v204, v204, v164
	v_add_f32_e32 v205, v205, v165
	v_add_f32_e32 v204, v204, v166
	v_add_f32_e32 v205, v205, v167
	v_cvt_pk_bf16_f32 v160, v160, v161
	v_cvt_pk_bf16_f32 v161, v162, v163
	v_cvt_pk_bf16_f32 v162, v164, v165
	v_cvt_pk_bf16_f32 v163, v166, v167
	v_exp_f32_e32 v168, v168
	v_exp_f32_e32 v169, v169
	s_waitcnt lgkmcnt(6)
	v_mfma_f32_32x32x16_bf16 v[16:31], v[64:67], v[160:163], v[16:31]
	v_exp_f32_e32 v170, v170
	v_exp_f32_e32 v171, v171
	v_exp_f32_e32 v172, v172
	s_waitcnt lgkmcnt(4)
	v_mfma_f32_32x32x16_bf16 v[0:15], v[68:71], v[160:163], v[0:15]
	v_exp_f32_e32 v173, v173
	v_exp_f32_e32 v174, v174
	v_exp_f32_e32 v175, v175
	v_add_f32_e32 v204, v204, v168
	v_add_f32_e32 v205, v205, v169
	v_add_f32_e32 v204, v204, v170
	v_add_f32_e32 v205, v205, v171
	v_add_f32_e32 v204, v204, v172
	v_add_f32_e32 v205, v205, v173
	v_add_f32_e32 v204, v204, v174
	v_add_f32_e32 v205, v205, v175
	v_cvt_pk_bf16_f32 v168, v168, v169
	v_cvt_pk_bf16_f32 v169, v170, v171
	v_cvt_pk_bf16_f32 v170, v172, v173
	v_cvt_pk_bf16_f32 v171, v174, v175
	s_nop 1
	s_waitcnt lgkmcnt(2)
	v_mfma_f32_32x32x16_bf16 v[16:31], v[72:75], v[168:171], v[16:31]
	s_waitcnt lgkmcnt(0)
	v_mfma_f32_32x32x16_bf16 v[0:15], v[76:79], v[168:171], v[0:15]
	s_waitcnt vmcnt(5)
	ds_write_b128 v198, v[120:123] offset:13312
	s_waitcnt vmcnt(4)
	ds_write_b128 v199, v[124:127] offset:13312
	s_waitcnt vmcnt(3)
	ds_write_b128 v200, v[128:131] offset:38912
	v_add_f32_e32 v204, v204, v205
	v_add_f32_e32 v203, v203, v204
	s_mov_b32 s6, 0x43800000
	s_cmp_eq_u32 s13, 0
	s_cselect_b32 s6, 0xbf800000, s6
	s_cbranch_scc1 .Lm1_rareA
	v_cmp_lt_f32_e32 vcc, 0x43000000, v204
	s_cbranch_vccz .Lm1_noresA
.Lm1_rareA:
	s_nop 15
	v_mov_b32_e32 v205, v204
	s_nop 1
	v_permlane32_swap_b32_e32 v204, v205
	v_add_f32_e32 v210, v204, v205
	v_cmp_lt_f32_e32 vcc, s6, v210
	v_frexp_exp_i32_f32_e32 v211, v210
	s_nop 1
	v_cndmask_b32_e32 v211, 0, v211, vcc
	v_cvt_f32_i32_e32 v212, v211
	v_sub_u32_e32 v211, 0, v211
	v_ldexp_f32 v210, 1.0, v211
	v_add_f32_e32 v202, v202, v212
	v_mul_f32_e32 v203, v203, v210
	v_mul_f32_e32 v0, v0, v210
	v_mul_f32_e32 v1, v1, v210
	v_mul_f32_e32 v2, v2, v210
	v_mul_f32_e32 v3, v3, v210
	v_mul_f32_e32 v4, v4, v210
	v_mul_f32_e32 v5, v5, v210
	v_mul_f32_e32 v6, v6, v210
	v_mul_f32_e32 v7, v7, v210
	v_mul_f32_e32 v8, v8, v210
	v_mul_f32_e32 v9, v9, v210
	v_mul_f32_e32 v10, v10, v210
	v_mul_f32_e32 v11, v11, v210
	v_mul_f32_e32 v12, v12, v210
	v_mul_f32_e32 v13, v13, v210
	v_mul_f32_e32 v14, v14, v210
	v_mul_f32_e32 v15, v15, v210
	v_mul_f32_e32 v16, v16, v210
	v_mul_f32_e32 v17, v17, v210
	v_mul_f32_e32 v18, v18, v210
	v_mul_f32_e32 v19, v19, v210
	v_mul_f32_e32 v20, v20, v210
	v_mul_f32_e32 v21, v21, v210
	v_mul_f32_e32 v22, v22, v210
	v_mul_f32_e32 v23, v23, v210
	v_mul_f32_e32 v24, v24, v210
	v_mul_f32_e32 v25, v25, v210
	v_mul_f32_e32 v26, v26, v210
	v_mul_f32_e32 v27, v27, v210
	v_mul_f32_e32 v28, v28, v210
	v_mul_f32_e32 v29, v29, v210
	v_mul_f32_e32 v30, v30, v210
	v_mul_f32_e32 v31, v31, v210
	v_sub_f32_e32 v32, 0, v202
	v_mov_b32_e32 v33, v32
	v_mov_b32_e32 v34, v32
	v_mov_b32_e32 v35, v32
	v_mov_b32_e32 v36, v32
	v_mov_b32_e32 v37, v32
	v_mov_b32_e32 v38, v32
	v_mov_b32_e32 v39, v32
	v_mov_b32_e32 v40, v32
	v_mov_b32_e32 v41, v32
	v_mov_b32_e32 v42, v32
	v_mov_b32_e32 v43, v32
	v_mov_b32_e32 v44, v32
	v_mov_b32_e32 v45, v32
	v_mov_b32_e32 v46, v32
	v_mov_b32_e32 v47, v32
.Lm1_noresA:
	s_waitcnt lgkmcnt(0)
	s_barrier
	ds_read_b128 v[48:51], v184 offset:13312
	ds_read_b128 v[52:55], v184 offset:13344
	ds_read_b128 v[56:59], v184 offset:13376
	ds_read_b128 v[60:63], v184 offset:13408
	ds_read_b128 v[64:67], v184 offset:13440
	ds_read_b128 v[68:71], v184 offset:13472
	ds_read_b128 v[72:75], v184 offset:19968
	ds_read_b128 v[76:79], v184 offset:20000
	ds_read_b128 v[80:83], v184 offset:20032
	ds_read_b128 v[84:87], v184 offset:20064
	ds_read_b128 v[88:91], v184 offset:20096
	ds_read_b128 v[92:95], v184 offset:20128
	s_min_u32 s6, s13, 32
	s_cmp_lt_u32 s13, 29
	s_cselect_b32 s7, 0, 0xffffffe0
	s_cselect_b32 s8, s15, s12
	s_add_i32 s6, s6, s7
	s_lshl_b32 s6, s6, 6
	s_add_i32 s8, s6, s8
	s_addk_i32 s8, 0xc0
	v_add_u32_e32 v208, s8, v194
	v_ashrrev_i32_e32 v209, 31, v208
	s_and_saveexec_b64 s[6:7], s[0:1]
	s_xor_b64 s[6:7], exec, s[6:7]
	v_mad_i64_i32 v[206:207], s[10:11], v208, s33, v[180:181]
	v_lshl_add_u64 v[206:207], v[206:207], 0, s[28:29]
	s_andn2_saveexec_b64 s[6:7], s[6:7]
	v_lshlrev_b64 v[206:207], 9, v[208:209]
	v_lshl_add_u64 v[206:207], v[182:183], 0, v[206:207]
	s_or_b64 exec, exec, s[6:7]
	global_load_dwordx4 v[120:123], v[206:207], off
	v_or_b32_e32 v208, s8, v195
	v_ashrrev_i32_e32 v209, 31, v208
	s_and_saveexec_b64 s[6:7], s[2:3]
	s_xor_b64 s[6:7], exec, s[6:7]
	v_mad_i64_i32 v[206:207], s[10:11], v208, s33, v[190:191]
	v_lshl_add_u64 v[206:207], v[206:207], 0, s[28:29]
	s_andn2_saveexec_b64 s[6:7], s[6:7]
	v_lshlrev_b64 v[206:207], 9, v[208:209]
	v_lshl_add_u64 v[206:207], v[192:193], 0, v[206:207]
	s_or_b64 exec, exec, s[6:7]
	global_load_dwordx4 v[124:127], v[206:207], off
	v_add_u32_e32 v206, s8, v196
	v_ashrrev_i32_e32 v207, 31, v206
	v_lshlrev_b64 v[206:207], 9, v[206:207]
	v_lshl_add_u64 v[206:207], v[178:179], 0, v[206:207]
	global_load_dwordx4 v[128:131], v[206:207], off
	s_waitcnt lgkmcnt(11)
	v_mfma_f32_32x32x16_bf16 v[144:159], v[48:51], v[96:99], v[32:47]
	s_waitcnt lgkmcnt(10)
	v_mfma_f32_32x32x16_bf16 v[144:159], v[52:55], v[100:103], v[144:159]
	s_waitcnt lgkmcnt(9)
	v_mfma_f32_32x32x16_bf16 v[144:159], v[56:59], v[104:107], v[144:159]
	s_waitcnt lgkmcnt(8)
	v_mfma_f32_32x32x16_bf16 v[144:159], v[60:63], v[108:111], v[144:159]
	s_waitcnt lgkmcnt(7)
	v_mfma_f32_32x32x16_bf16 v[144:159], v[64:67], v[112:115], v[144:159]
	s_waitcnt lgkmcnt(6)
	v_mfma_f32_32x32x16_bf16 v[144:159], v[68:71], v[116:119], v[144:159]
	s_waitcnt lgkmcnt(5)
	v_mfma_f32_32x32x16_bf16 v[160:175], v[72:75], v[96:99], v[32:47]
	s_waitcnt lgkmcnt(4)
	v_mfma_f32_32x32x16_bf16 v[160:175], v[76:79], v[100:103], v[160:175]
	s_waitcnt lgkmcnt(3)
	v_mfma_f32_32x32x16_bf16 v[160:175], v[80:83], v[104:107], v[160:175]
	s_waitcnt lgkmcnt(2)
	v_mfma_f32_32x32x16_bf16 v[160:175], v[84:87], v[108:111], v[160:175]
	s_waitcnt lgkmcnt(1)
	v_mfma_f32_32x32x16_bf16 v[160:175], v[88:91], v[112:115], v[160:175]
	s_waitcnt lgkmcnt(0)
	v_mfma_f32_32x32x16_bf16 v[160:175], v[92:95], v[116:119], v[160:175]
	ds_read_b64_tr_b16 v[48:49], v201 offset:38912
	ds_read_b64_tr_b16 v[50:51], v201 offset:40448
	ds_read_b64_tr_b16 v[52:53], v201 offset:38976
	ds_read_b64_tr_b16 v[54:55], v201 offset:40512
	ds_read_b64_tr_b16 v[56:57], v201 offset:41984
	ds_read_b64_tr_b16 v[58:59], v201 offset:43520
	ds_read_b64_tr_b16 v[60:61], v201 offset:42048
	ds_read_b64_tr_b16 v[62:63], v201 offset:43584
	ds_read_b64_tr_b16 v[64:65], v201 offset:45056
	ds_read_b64_tr_b16 v[66:67], v201 offset:46592
	ds_read_b64_tr_b16 v[68:69], v201 offset:45120
	ds_read_b64_tr_b16 v[70:71], v201 offset:46656
	ds_read_b64_tr_b16 v[72:73], v201 offset:48128
	ds_read_b64_tr_b16 v[74:75], v201 offset:49664
	ds_read_b64_tr_b16 v[76:77], v201 offset:48192
	ds_read_b64_tr_b16 v[78:79], v201 offset:49728
	v_exp_f32_e32 v144, v144
	v_exp_f32_e32 v145, v145
	v_exp_f32_e32 v146, v146
	v_exp_f32_e32 v147, v147
	v_exp_f32_e32 v148, v148
	v_exp_f32_e32 v149, v149
	v_exp_f32_e32 v150, v150
	v_exp_f32_e32 v151, v151
	v_add_f32_e32 v204, v144, v146
	v_add_f32_e32 v205, v145, v147
	v_add_f32_e32 v204, v204, v148
	v_add_f32_e32 v205, v205, v149
	v_add_f32_e32 v204, v204, v150
	v_add_f32_e32 v205, v205, v151
	v_cvt_pk_bf16_f32 v144, v144, v145
	v_cvt_pk_bf16_f32 v145, v146, v147
	v_cvt_pk_bf16_f32 v146, v148, v149
	v_cvt_pk_bf16_f32 v147, v150, v151
	v_exp_f32_e32 v152, v152
	v_exp_f32_e32 v153, v153
	s_waitcnt lgkmcnt(14)
	v_mfma_f32_32x32x16_bf16 v[16:31], v[48:51], v[144:147], v[16:31]
	v_exp_f32_e32 v154, v154
	v_exp_f32_e32 v155, v155
	v_exp_f32_e32 v156, v156
	s_waitcnt lgkmcnt(12)
	v_mfma_f32_32x32x16_bf16 v[0:15], v[52:55], v[144:147], v[0:15]
	v_exp_f32_e32 v157, v157
	v_exp_f32_e32 v158, v158
	v_exp_f32_e32 v159, v159
	v_add_f32_e32 v204, v204, v152
	v_add_f32_e32 v205, v205, v153
	v_add_f32_e32 v204, v204, v154
	v_add_f32_e32 v205, v205, v155
	v_add_f32_e32 v204, v204, v156
	v_add_f32_e32 v205, v205, v157
	v_add_f32_e32 v204, v204, v158
	v_add_f32_e32 v205, v205, v159
	v_cvt_pk_bf16_f32 v152, v152, v153
	v_cvt_pk_bf16_f32 v153, v154, v155
	v_cvt_pk_bf16_f32 v154, v156, v157
	v_cvt_pk_bf16_f32 v155, v158, v159
	v_exp_f32_e32 v160, v160
	v_exp_f32_e32 v161, v161
	s_waitcnt lgkmcnt(10)
	v_mfma_f32_32x32x16_bf16 v[16:31], v[56:59], v[152:155], v[16:31]
	v_exp_f32_e32 v162, v162
	v_exp_f32_e32 v163, v163
	v_exp_f32_e32 v164, v164
	s_waitcnt lgkmcnt(8)
	v_mfma_f32_32x32x16_bf16 v[0:15], v[60:63], v[152:155], v[0:15]
	v_exp_f32_e32 v165, v165
	v_exp_f32_e32 v166, v166
	v_exp_f32_e32 v167, v167
	v_add_f32_e32 v204, v204, v160
	v_add_f32_e32 v205, v205, v161
	v_add_f32_e32 v204, v204, v162
	v_add_f32_e32 v205, v205, v163
	v_add_f32_e32 v204, v204, v164
	v_add_f32_e32 v205, v205, v165
	v_add_f32_e32 v204, v204, v166
	v_add_f32_e32 v205, v205, v167
	v_cvt_pk_bf16_f32 v160, v160, v161
	v_cvt_pk_bf16_f32 v161, v162, v163
	v_cvt_pk_bf16_f32 v162, v164, v165
	v_cvt_pk_bf16_f32 v163, v166, v167
	v_exp_f32_e32 v168, v168
	v_exp_f32_e32 v169, v169
	s_waitcnt lgkmcnt(6)
	v_mfma_f32_32x32x16_bf16 v[16:31], v[64:67], v[160:163], v[16:31]
	v_exp_f32_e32 v170, v170
	v_exp_f32_e32 v171, v171
	v_exp_f32_e32 v172, v172
	s_waitcnt lgkmcnt(4)
	v_mfma_f32_32x32x16_bf16 v[0:15], v[68:71], v[160:163], v[0:15]
	v_exp_f32_e32 v173, v173
	v_exp_f32_e32 v174, v174
	v_exp_f32_e32 v175, v175
	v_add_f32_e32 v204, v204, v168
	v_add_f32_e32 v205, v205, v169
	v_add_f32_e32 v204, v204, v170
	v_add_f32_e32 v205, v205, v171
	v_add_f32_e32 v204, v204, v172
	v_add_f32_e32 v205, v205, v173
	v_add_f32_e32 v204, v204, v174
	v_add_f32_e32 v205, v205, v175
	v_cvt_pk_bf16_f32 v168, v168, v169
	v_cvt_pk_bf16_f32 v169, v170, v171
	v_cvt_pk_bf16_f32 v170, v172, v173
	v_cvt_pk_bf16_f32 v171, v174, v175
	s_nop 1
	s_waitcnt lgkmcnt(2)
	v_mfma_f32_32x32x16_bf16 v[16:31], v[72:75], v[168:171], v[16:31]
	s_waitcnt lgkmcnt(0)
	v_mfma_f32_32x32x16_bf16 v[0:15], v[76:79], v[168:171], v[0:15]
	s_cmp_gt_u32 s13, 33
	s_cbranch_scc1 .Lm1_skipw
	s_waitcnt vmcnt(5)
	ds_write_b128 v198, v[132:135]
	s_waitcnt vmcnt(4)
	ds_write_b128 v199, v[136:139]
	s_waitcnt vmcnt(3)
	ds_write_b128 v200, v[140:143] offset:26624
.Lm1_skipw:
	v_add_f32_e32 v204, v204, v205
	v_add_f32_e32 v203, v203, v204
	s_mov_b32 s6, 0x43800000
	v_cmp_lt_f32_e32 vcc, 0x43000000, v204
	s_cbranch_vccz .Lm1_noresB

.Lm1_noresB:
	s_waitcnt lgkmcnt(0)
	s_barrier
	s_cmp_gt_u32 s13, 33
	s_cbranch_scc1 .LBB0_765
	s_add_i32 s13, s13, 2
	s_branch .LBB0_783

.LBB0_903:
	v_mov_b32_e32 v64, 0
	v_mov_b32_e32 v65, 0
	v_readlane_b32 s26, v255, 31
	v_readlane_b32 s27, v255, 32
	ds_read_b32 v65, v177
	ds_read_b32 v64, v177 offset:128
	v_mov_b32_e32 v66, 0
	v_mov_b32_e32 v67, 0
	v_readlane_b32 s26, v255, 35
	v_readlane_b32 s27, v255, 36
	ds_read_b32 v67, v177 offset:4
	ds_read_b32 v66, v177 offset:132
	v_mov_b32_e32 v68, 0
	v_mov_b32_e32 v69, 0
	ds_read_b32 v69, v177 offset:8
	ds_read_b32 v68, v177 offset:136
	v_mov_b32_e32 v70, 0
	v_mov_b32_e32 v71, 0
	ds_read_b32 v71, v177 offset:12
	ds_read_b32 v70, v177 offset:140
	v_mov_b32_e32 v72, 0
	v_mov_b32_e32 v73, 0
	ds_read_b32 v73, v177 offset:32
	ds_read_b32 v72, v177 offset:160
	v_mov_b32_e32 v74, 0
	v_mov_b32_e32 v75, 0
	ds_read_b32 v75, v177 offset:36
	ds_read_b32 v74, v177 offset:164
	v_mov_b32_e32 v76, 0
	v_mov_b32_e32 v77, 0
	ds_read_b32 v77, v177 offset:40
	ds_read_b32 v76, v177 offset:168
	v_mov_b32_e32 v78, 0
	v_mov_b32_e32 v79, 0
	ds_read_b32 v79, v177 offset:44
	ds_read_b32 v78, v177 offset:172
	v_mov_b32_e32 v80, 0
	v_mov_b32_e32 v81, 0
	ds_read_b32 v81, v177 offset:64
	ds_read_b32 v80, v177 offset:192
	v_mov_b32_e32 v82, 0
	v_mov_b32_e32 v83, 0
	ds_read_b32 v83, v177 offset:68
	ds_read_b32 v82, v177 offset:196
	v_mov_b32_e32 v84, 0
	v_mov_b32_e32 v85, 0
	ds_read_b32 v85, v177 offset:72
	ds_read_b32 v84, v177 offset:200
	v_mov_b32_e32 v86, 0
	v_mov_b32_e32 v87, 0
	ds_read_b32 v87, v177 offset:76
	ds_read_b32 v86, v177 offset:204
	v_mov_b32_e32 v88, 0
	v_mov_b32_e32 v89, 0
	ds_read_b32 v89, v177 offset:96
	ds_read_b32 v88, v177 offset:224
	v_mov_b32_e32 v90, 0
	v_mov_b32_e32 v91, 0
	ds_read_b32 v91, v177 offset:100
	ds_read_b32 v90, v177 offset:228
	v_mov_b32_e32 v92, 0
	v_mov_b32_e32 v93, 0
	ds_read_b32 v93, v177 offset:104
	ds_read_b32 v92, v177 offset:232
	v_mov_b32_e32 v94, 0
	v_mov_b32_e32 v95, 0
	ds_read_b32 v95, v177 offset:108
	ds_read_b32 v94, v177 offset:236
	v_readlane_b32 s24, v255, 33
	s_waitcnt lgkmcnt(0)
	v_fmac_f32_e32 v65, 0x3e38aa3b, v48
	v_fmac_f32_e32 v64, 0x3e38aa3b, v32
	v_fmac_f32_e32 v67, 0x3e38aa3b, v49
	v_readlane_b32 s25, v255, 34
	v_fmac_f32_e32 v66, 0x3e38aa3b, v33
	v_cndmask_b32_e64 v48, v65, v238, s[40:41]
	v_cndmask_b32_e64 v32, v238, v64, s[42:43]
	v_cndmask_b32_e64 v49, v67, v238, s[24:25]
	v_cndmask_b32_e64 v33, v238, v66, s[48:49]
	v_max_f32_e32 v64, v48, v32
	v_max_f32_e32 v65, v49, v33
	s_mov_b32 s24, 0xf149f2ca
	v_max3_f32 v64, v64, s24, v65
	v_readlane_b32 s24, v255, 37
	v_fmac_f32_e32 v69, 0x3e38aa3b, v50
	v_readlane_b32 s25, v255, 38
	v_fmac_f32_e32 v68, 0x3e38aa3b, v34
	v_fmac_f32_e32 v71, 0x3e38aa3b, v51
	v_fmac_f32_e32 v70, 0x3e38aa3b, v35
	v_cndmask_b32_e64 v50, v69, v238, s[24:25]
	v_cndmask_b32_e64 v34, v238, v68, s[54:55]
	v_cndmask_b32_e64 v51, v71, v238, s[56:57]
	v_cndmask_b32_e64 v35, v238, v70, s[60:61]
	v_fmac_f32_e32 v73, 0x3e38aa3b, v52
	v_fmac_f32_e32 v72, 0x3e38aa3b, v36
	v_fmac_f32_e32 v75, 0x3e38aa3b, v53
	v_fmac_f32_e32 v74, 0x3e38aa3b, v37
	v_max_f32_e32 v65, v50, v34
	v_max_f32_e32 v66, v51, v35
	v_cndmask_b32_e64 v52, v73, v238, s[62:63]
	v_cndmask_b32_e64 v36, v238, v72, s[66:67]
	v_cndmask_b32_e64 v53, v75, v238, s[68:69]
	v_cndmask_b32_e64 v37, v238, v74, s[72:73]
	v_fmac_f32_e32 v77, 0x3e38aa3b, v54
	v_fmac_f32_e32 v76, 0x3e38aa3b, v38
	v_fmac_f32_e32 v79, 0x3e38aa3b, v55
	v_fmac_f32_e32 v78, 0x3e38aa3b, v39
	v_max3_f32 v64, v64, v65, v66
	v_max_f32_e32 v65, v52, v36
	v_max_f32_e32 v66, v53, v37
	v_cndmask_b32_e64 v54, v77, v238, s[74:75]
	v_cndmask_b32_e64 v38, v238, v76, s[78:79]
	v_cndmask_b32_e64 v55, v79, v238, s[80:81]
	v_cndmask_b32_e64 v39, v238, v78, s[84:85]
	v_fmac_f32_e32 v81, 0x3e38aa3b, v56
	v_fmac_f32_e32 v80, 0x3e38aa3b, v40
	v_fmac_f32_e32 v83, 0x3e38aa3b, v57
	v_fmac_f32_e32 v82, 0x3e38aa3b, v41
	v_max3_f32 v64, v64, v65, v66
	v_max_f32_e32 v65, v54, v38
	v_max_f32_e32 v66, v55, v39
	v_cndmask_b32_e64 v56, v238, v81, s[86:87]
	v_cndmask_b32_e64 v40, v238, v80, s[88:89]
	v_cndmask_b32_e64 v57, v238, v83, s[90:91]
	v_cndmask_b32_e64 v41, v238, v82, s[92:93]
	v_fmac_f32_e32 v85, 0x3e38aa3b, v58
	v_fmac_f32_e32 v84, 0x3e38aa3b, v42
	v_fmac_f32_e32 v87, 0x3e38aa3b, v59
	v_fmac_f32_e32 v86, 0x3e38aa3b, v43
	v_max3_f32 v64, v64, v65, v66
	v_max_f32_e32 v65, v56, v40
	v_max_f32_e32 v66, v57, v41
	v_cndmask_b32_e64 v58, v238, v85, s[94:95]
	v_cndmask_b32_e64 v42, v238, v84, s[96:97]
	v_cndmask_b32_e64 v59, v238, v87, s[0:1]
	v_cndmask_b32_e64 v43, v238, v86, s[2:3]
	v_fmac_f32_e32 v89, 0x3e38aa3b, v60
	v_fmac_f32_e32 v88, 0x3e38aa3b, v44
	v_fmac_f32_e32 v91, 0x3e38aa3b, v61
	v_fmac_f32_e32 v90, 0x3e38aa3b, v45
	v_max3_f32 v64, v64, v65, v66
	v_max_f32_e32 v65, v58, v42
	v_max_f32_e32 v66, v59, v43
	v_cndmask_b32_e64 v60, v238, v89, s[4:5]
	v_cndmask_b32_e64 v44, v238, v88, s[6:7]
	v_cndmask_b32_e64 v61, v238, v91, s[8:9]
	v_cndmask_b32_e64 v45, v238, v90, s[10:11]
	v_fmac_f32_e32 v93, 0x3e38aa3b, v62
	v_fmac_f32_e32 v92, 0x3e38aa3b, v46
	v_fmac_f32_e32 v95, 0x3e38aa3b, v63
	v_fmac_f32_e32 v94, 0x3e38aa3b, v47
	v_max3_f32 v64, v64, v65, v66
	v_max_f32_e32 v65, v60, v44
	v_max_f32_e32 v66, v61, v45
	v_cndmask_b32_e64 v62, v238, v93, s[12:13]
	v_cndmask_b32_e64 v46, v238, v92, s[14:15]
	v_cndmask_b32_e64 v63, v238, v95, s[16:17]
	v_cndmask_b32_e64 v47, v238, v94, s[18:19]
	v_max3_f32 v64, v64, v65, v66
	v_max_f32_e32 v65, v62, v46
	v_max_f32_e32 v66, v63, v47
	v_max3_f32 v64, v64, v65, v66
	v_mov_b32_e32 v65, v64
	s_nop 1
	v_permlane32_swap_b32_e32 v64, v65
	v_max_f32_e32 v65, v65, v65
	v_max_f32_e32 v64, v64, v64
	v_max_f32_e32 v64, v64, v65
	v_cmp_gt_f32_e32 vcc, v64, v179
	s_cmp_eq_u64 vcc, 0
	v_max_f32_e32 v64, v178, v64
	s_cselect_b64 vcc, -1, 0
	v_cndmask_b32_e32 v170, v64, v168, vcc
	v_sub_f32_e32 v32, v32, v170
	v_exp_f32_e32 v80, v32
	v_sub_f32_e32 v32, v49, v170
	v_exp_f32_e32 v65, v32
	v_sub_f32_e32 v32, v33, v170
	v_exp_f32_e32 v81, v32
	v_sub_f32_e32 v32, v50, v170
	v_exp_f32_e32 v66, v32
	v_sub_f32_e32 v32, v34, v170
	v_exp_f32_e32 v82, v32
	v_sub_f32_e32 v32, v51, v170
	v_exp_f32_e32 v67, v32
	v_sub_f32_e32 v32, v35, v170
	v_exp_f32_e32 v83, v32
	v_sub_f32_e32 v32, v52, v170
	v_exp_f32_e32 v68, v32
	v_sub_f32_e32 v32, v36, v170
	v_exp_f32_e32 v84, v32
	v_sub_f32_e32 v32, v53, v170
	v_exp_f32_e32 v69, v32
	v_sub_f32_e32 v32, v37, v170
	v_exp_f32_e32 v85, v32
	v_sub_f32_e32 v32, v54, v170
	v_exp_f32_e32 v70, v32
	v_sub_f32_e32 v32, v38, v170
	v_exp_f32_e32 v86, v32
	v_sub_f32_e32 v32, v55, v170
	v_exp_f32_e32 v71, v32
	v_sub_f32_e32 v32, v39, v170
	v_exp_f32_e32 v87, v32
	v_sub_f32_e32 v32, v56, v170
	v_exp_f32_e32 v72, v32
	v_sub_f32_e32 v32, v40, v170
	v_exp_f32_e32 v88, v32
	v_sub_f32_e32 v32, v57, v170
	v_exp_f32_e32 v73, v32
	v_sub_f32_e32 v32, v41, v170
	v_exp_f32_e32 v89, v32
	v_sub_f32_e32 v32, v58, v170
	v_exp_f32_e32 v74, v32
	v_sub_f32_e32 v32, v42, v170
	v_exp_f32_e32 v90, v32
	v_sub_f32_e32 v32, v59, v170
	v_exp_f32_e32 v75, v32
	v_sub_f32_e32 v32, v43, v170
	v_exp_f32_e32 v91, v32
	v_sub_f32_e32 v32, v60, v170
	v_exp_f32_e32 v76, v32
	v_sub_f32_e32 v32, v44, v170
	v_exp_f32_e32 v92, v32
	v_sub_f32_e32 v32, v61, v170
	v_exp_f32_e32 v77, v32
	v_sub_f32_e32 v32, v45, v170
	v_exp_f32_e32 v93, v32
	v_sub_f32_e32 v32, v62, v170
	v_exp_f32_e32 v78, v32
	v_sub_f32_e32 v32, v46, v170
	v_sub_f32_e32 v48, v48, v170
	v_exp_f32_e32 v94, v32
	v_sub_f32_e32 v32, v63, v170
	v_exp_f32_e32 v64, v48
	v_exp_f32_e32 v79, v32
	v_sub_f32_e32 v95, v47, v170
	v_cmp_gt_f32_e32 vcc, v170, v168
	s_cbranch_vccnz .LBB0_884
	s_branch .LBB0_885

.LBB0_969:
	v_mov_b32_e32 v64, 0
	v_mov_b32_e32 v65, 0
	v_readlane_b32 s26, v255, 31
	v_readlane_b32 s27, v255, 32
	ds_read_b32 v65, v177 offset:124
	ds_read_b32 v64, v177 offset:252
	v_mov_b32_e32 v66, 0
	v_mov_b32_e32 v67, 0
	v_readlane_b32 s26, v255, 35
	v_readlane_b32 s27, v255, 36
	ds_read_b32 v67, v177 offset:128
	ds_read_b32 v66, v177 offset:256
	v_mov_b32_e32 v68, 0
	v_mov_b32_e32 v69, 0
	ds_read_b32 v69, v177 offset:132
	ds_read_b32 v68, v177 offset:260
	v_mov_b32_e32 v70, 0
	v_mov_b32_e32 v71, 0
	ds_read_b32 v71, v177 offset:136
	ds_read_b32 v70, v177 offset:264
	v_mov_b32_e32 v72, 0
	v_mov_b32_e32 v73, 0
	ds_read_b32 v73, v177 offset:156
	ds_read_b32 v72, v177 offset:284
	v_mov_b32_e32 v74, 0
	v_mov_b32_e32 v75, 0
	ds_read_b32 v75, v177 offset:160
	ds_read_b32 v74, v177 offset:288
	v_mov_b32_e32 v76, 0
	v_mov_b32_e32 v77, 0
	ds_read_b32 v77, v177 offset:164
	ds_read_b32 v76, v177 offset:292
	v_mov_b32_e32 v78, 0
	v_mov_b32_e32 v79, 0
	ds_read_b32 v79, v177 offset:168
	ds_read_b32 v78, v177 offset:296
	v_mov_b32_e32 v80, 0
	v_mov_b32_e32 v81, 0
	ds_read_b32 v81, v177 offset:188
	ds_read_b32 v80, v177 offset:316
	v_mov_b32_e32 v82, 0
	v_mov_b32_e32 v83, 0
	ds_read_b32 v83, v177 offset:192
	ds_read_b32 v82, v177 offset:320
	v_mov_b32_e32 v84, 0
	v_mov_b32_e32 v85, 0
	ds_read_b32 v85, v177 offset:196
	ds_read_b32 v84, v177 offset:324
	v_mov_b32_e32 v86, 0
	v_mov_b32_e32 v87, 0
	ds_read_b32 v87, v177 offset:200
	ds_read_b32 v86, v177 offset:328
	v_mov_b32_e32 v88, 0
	v_mov_b32_e32 v89, 0
	ds_read_b32 v89, v177 offset:220
	ds_read_b32 v88, v177 offset:348
	v_mov_b32_e32 v90, 0
	v_mov_b32_e32 v91, 0
	ds_read_b32 v91, v177 offset:224
	ds_read_b32 v90, v177 offset:352
	v_mov_b32_e32 v92, 0
	v_mov_b32_e32 v93, 0
	ds_read_b32 v93, v177 offset:228
	ds_read_b32 v92, v177 offset:356
	v_mov_b32_e32 v94, 0
	v_mov_b32_e32 v95, 0
	ds_read_b32 v95, v177 offset:232
	ds_read_b32 v94, v177 offset:360
	v_readlane_b32 s24, v255, 33
	s_waitcnt lgkmcnt(0)
	v_fmac_f32_e32 v65, 0x3e38aa3b, v48
	v_fmac_f32_e32 v64, 0x3e38aa3b, v32
	v_fmac_f32_e32 v67, 0x3e38aa3b, v49
	v_readlane_b32 s25, v255, 34
	v_fmac_f32_e32 v66, 0x3e38aa3b, v33
	v_cndmask_b32_e64 v48, v65, v238, s[40:41]
	v_cndmask_b32_e64 v32, v238, v64, s[42:43]
	v_cndmask_b32_e64 v49, v67, v238, s[24:25]
	v_cndmask_b32_e64 v33, v238, v66, s[48:49]
	v_max_f32_e32 v64, v48, v32
	v_max_f32_e32 v65, v49, v33
	s_mov_b32 s24, 0xf149f2ca
	v_max3_f32 v64, v64, s24, v65
	v_readlane_b32 s24, v255, 37
	v_fmac_f32_e32 v69, 0x3e38aa3b, v50
	v_readlane_b32 s25, v255, 38
	v_fmac_f32_e32 v68, 0x3e38aa3b, v34
	v_fmac_f32_e32 v71, 0x3e38aa3b, v51
	v_fmac_f32_e32 v70, 0x3e38aa3b, v35
	v_cndmask_b32_e64 v50, v69, v238, s[24:25]
	v_cndmask_b32_e64 v34, v238, v68, s[54:55]
	v_cndmask_b32_e64 v51, v71, v238, s[56:57]
	v_cndmask_b32_e64 v35, v238, v70, s[60:61]
	v_fmac_f32_e32 v73, 0x3e38aa3b, v52
	v_fmac_f32_e32 v72, 0x3e38aa3b, v36
	v_fmac_f32_e32 v75, 0x3e38aa3b, v53
	v_fmac_f32_e32 v74, 0x3e38aa3b, v37
	v_max_f32_e32 v65, v50, v34
	v_max_f32_e32 v66, v51, v35
	v_cndmask_b32_e64 v52, v73, v238, s[62:63]
	v_cndmask_b32_e64 v36, v238, v72, s[66:67]
	v_cndmask_b32_e64 v53, v75, v238, s[68:69]
	v_cndmask_b32_e64 v37, v238, v74, s[72:73]
	v_fmac_f32_e32 v77, 0x3e38aa3b, v54
	v_fmac_f32_e32 v76, 0x3e38aa3b, v38
	v_fmac_f32_e32 v79, 0x3e38aa3b, v55
	v_fmac_f32_e32 v78, 0x3e38aa3b, v39
	v_max3_f32 v64, v64, v65, v66
	v_max_f32_e32 v65, v52, v36
	v_max_f32_e32 v66, v53, v37
	v_cndmask_b32_e64 v54, v77, v238, s[74:75]
	v_cndmask_b32_e64 v38, v238, v76, s[78:79]
	v_cndmask_b32_e64 v55, v79, v238, s[80:81]
	v_cndmask_b32_e64 v39, v238, v78, s[84:85]
	v_fmac_f32_e32 v81, 0x3e38aa3b, v56
	v_fmac_f32_e32 v80, 0x3e38aa3b, v40
	v_fmac_f32_e32 v83, 0x3e38aa3b, v57
	v_fmac_f32_e32 v82, 0x3e38aa3b, v41
	v_max3_f32 v64, v64, v65, v66
	v_max_f32_e32 v65, v54, v38
	v_max_f32_e32 v66, v55, v39
	v_cndmask_b32_e64 v56, v238, v81, s[86:87]
	v_cndmask_b32_e64 v40, v238, v80, s[88:89]
	v_cndmask_b32_e64 v57, v238, v83, s[90:91]
	v_cndmask_b32_e64 v41, v238, v82, s[92:93]
	v_fmac_f32_e32 v85, 0x3e38aa3b, v58
	v_fmac_f32_e32 v84, 0x3e38aa3b, v42
	v_fmac_f32_e32 v87, 0x3e38aa3b, v59
	v_fmac_f32_e32 v86, 0x3e38aa3b, v43
	v_max3_f32 v64, v64, v65, v66
	v_max_f32_e32 v65, v56, v40
	v_max_f32_e32 v66, v57, v41
	v_cndmask_b32_e64 v58, v238, v85, s[94:95]
	v_cndmask_b32_e64 v42, v238, v84, s[96:97]
	v_cndmask_b32_e64 v59, v238, v87, s[0:1]
	v_cndmask_b32_e64 v43, v238, v86, s[2:3]
	v_fmac_f32_e32 v89, 0x3e38aa3b, v60
	v_fmac_f32_e32 v88, 0x3e38aa3b, v44
	v_fmac_f32_e32 v91, 0x3e38aa3b, v61
	v_fmac_f32_e32 v90, 0x3e38aa3b, v45
	v_max3_f32 v64, v64, v65, v66
	v_max_f32_e32 v65, v58, v42
	v_max_f32_e32 v66, v59, v43
	v_cndmask_b32_e64 v60, v238, v89, s[4:5]
	v_cndmask_b32_e64 v44, v238, v88, s[6:7]
	v_cndmask_b32_e64 v61, v238, v91, s[8:9]
	v_cndmask_b32_e64 v45, v238, v90, s[10:11]
	v_fmac_f32_e32 v93, 0x3e38aa3b, v62
	v_fmac_f32_e32 v92, 0x3e38aa3b, v46
	v_fmac_f32_e32 v95, 0x3e38aa3b, v63
	v_fmac_f32_e32 v94, 0x3e38aa3b, v47
	v_max3_f32 v64, v64, v65, v66
	v_max_f32_e32 v65, v60, v44
	v_max_f32_e32 v66, v61, v45
	v_cndmask_b32_e64 v62, v238, v93, s[12:13]
	v_cndmask_b32_e64 v46, v238, v92, s[14:15]
	v_cndmask_b32_e64 v63, v238, v95, s[16:17]
	v_cndmask_b32_e64 v47, v238, v94, s[18:19]
	v_max3_f32 v64, v64, v65, v66
	v_max_f32_e32 v65, v62, v46
	v_max_f32_e32 v66, v63, v47
	v_max3_f32 v64, v64, v65, v66
	v_mov_b32_e32 v65, v64
	s_nop 1
	v_permlane32_swap_b32_e32 v64, v65
	v_max_f32_e32 v65, v65, v65
	v_max_f32_e32 v64, v64, v64
	v_max_f32_e32 v64, v64, v65
	v_cmp_gt_f32_e32 vcc, v64, v179
	s_cmp_eq_u64 vcc, 0
	v_max_f32_e32 v64, v178, v64
	s_cselect_b64 vcc, -1, 0
	v_cndmask_b32_e32 v168, v64, v170, vcc
	v_sub_f32_e32 v32, v32, v168
	v_exp_f32_e32 v80, v32
	v_sub_f32_e32 v32, v49, v168
	v_exp_f32_e32 v65, v32
	v_sub_f32_e32 v32, v33, v168
	v_exp_f32_e32 v81, v32
	v_sub_f32_e32 v32, v50, v168
	v_exp_f32_e32 v66, v32
	v_sub_f32_e32 v32, v34, v168
	v_exp_f32_e32 v82, v32
	v_sub_f32_e32 v32, v51, v168
	v_exp_f32_e32 v67, v32
	v_sub_f32_e32 v32, v35, v168
	v_exp_f32_e32 v83, v32
	v_sub_f32_e32 v32, v52, v168
	v_exp_f32_e32 v68, v32
	v_sub_f32_e32 v32, v36, v168
	v_exp_f32_e32 v84, v32
	v_sub_f32_e32 v32, v53, v168
	v_exp_f32_e32 v69, v32
	v_sub_f32_e32 v32, v37, v168
	v_exp_f32_e32 v85, v32
	v_sub_f32_e32 v32, v54, v168
	v_exp_f32_e32 v70, v32
	v_sub_f32_e32 v32, v38, v168
	v_exp_f32_e32 v86, v32
	v_sub_f32_e32 v32, v55, v168
	v_exp_f32_e32 v71, v32
	v_sub_f32_e32 v32, v39, v168
	v_exp_f32_e32 v87, v32
	v_sub_f32_e32 v32, v56, v168
	v_exp_f32_e32 v72, v32
	v_sub_f32_e32 v32, v40, v168
	v_exp_f32_e32 v88, v32
	v_sub_f32_e32 v32, v57, v168
	v_exp_f32_e32 v73, v32
	v_sub_f32_e32 v32, v41, v168
	v_exp_f32_e32 v89, v32
	v_sub_f32_e32 v32, v58, v168
	v_exp_f32_e32 v74, v32
	v_sub_f32_e32 v32, v42, v168
	v_exp_f32_e32 v90, v32
	v_sub_f32_e32 v32, v59, v168
	v_exp_f32_e32 v75, v32
	v_sub_f32_e32 v32, v43, v168
	v_exp_f32_e32 v91, v32
	v_sub_f32_e32 v32, v60, v168
	v_exp_f32_e32 v76, v32
	v_sub_f32_e32 v32, v44, v168
	v_exp_f32_e32 v92, v32
	v_sub_f32_e32 v32, v61, v168
	v_exp_f32_e32 v77, v32
	v_sub_f32_e32 v32, v45, v168
	v_exp_f32_e32 v93, v32
	v_sub_f32_e32 v32, v62, v168
	v_exp_f32_e32 v78, v32
	v_sub_f32_e32 v32, v46, v168
	v_sub_f32_e32 v48, v48, v168
	v_exp_f32_e32 v94, v32
	v_sub_f32_e32 v32, v63, v168
	v_exp_f32_e32 v64, v48
	v_exp_f32_e32 v79, v32
	v_sub_f32_e32 v95, v47, v168
	v_cmp_gt_f32_e32 vcc, v168, v170
	s_cbranch_vccnz .LBB0_896
	s_branch .LBB0_897
